# write-through bf16 epilogue stores except the last quarter of the second tile (short ack wait before the phase barrier)
# baseline (speedup 1.0000x reference)
;     ...
;     auto compute = [&](int cb, bool do_issue, int ikt, int ib) {
;         const char* base = lds + cb * BUF;
;         bf16x8 af[MT], bfr[NT];
; #pragma unroll
;         for (int nt = 0; nt < NT; ++nt) {
;             const int br = BM + (nt / NTS) * (BN / NSEG) + wc * (NTS * 16) + (nt % NTS) * 16;
;             bfr[nt] = *(const bf16x8*)(base + (br + l15) * 64 + rsw);
;         }
; #pragma unroll
;         for (int mt = 0; mt < MT; ++mt) af[mt] = *(const bf16x8*)(base + (wr * WM + mt * 16 + l15) * 64 + rsw);
;         constexpr int TOT = MT * NT, PER = (TOT + NIT - 1) / NIT;
; #pragma unroll
;         for (int part = 0; part < NIT; ++part) {
; #pragma unroll
;             for (int q = 0; q < PER; ++q) {
;                 const int idx = part * PER + q;
;                 if (idx < TOT) {
;                     const int mt = idx / NT, nt = idx % NT;
;                     acc[mt][nt] = SWAP ? mfma16(bfr[nt], af[mt], acc[mt][nt]) : mfma16(af[mt], bfr[nt], acc[mt][nt]);
;                 }
;             }
;             __builtin_amdgcn_sched_barrier(0);
;             if (do_issue) issue_one(ikt, ib, part);
;             __builtin_amdgcn_sched_barrier(0);
;         }
; DI void unit_O(const Params& p, char* lds, int l, int tile, int glu_tiles, int tile_b) {
;     ...
;     auto issue_x = [&](int half) {
;         if (l == 0) {
; #pragma unroll 1
;             for (int i = 0; i < 16; ++i) {
;                 const int pc = (wid * 16 + i + xrot) & 127, row = pc >> 2, phys = (pc & 3) * 64 + lane, logical = phys ^ (row & 15);
;                 __builtin_amdgcn_global_load_lds((const unsigned*)(xres + (r0 + half * 32 + row) * 1024 + logical * 4), (unsigned*)(XR + pc * 1024 + lane * 16), 16, 0, 0);
;             }
;         } else {
; #pragma unroll 1
;             for (int i = 0; i < 8; ++i) {
;                 const int pc = (wid * 8 + i + (xrot >> 1)) & 63, kt = pc >> 1, sub = pc & 1;
;                 __builtin_amdgcn_global_load_lds((const unsigned*)(xbres + ((size_t)kt * 128 + half * 32) * 32 + sub * 512 + lane * 8), (unsigned*)(XR + pc * 1024 + lane * 16), 16, 0, 0);
;             }
;         }
;     };
;     issue_x(0);
;     {
;         const float* gsrc = (tid < 256) ? (p.ln_g + l * 1024 + tid * 4) : (p.ln_b + l * 1024 + (tid - 256) * 4);
;         *(f32x4*)(GB + tid * 4) = *(const f32x4*)gsrc;
;     }
;     float* xo = (l == 0) ? WS_PTR(float, OFF_X1) : p.out;
.Lpo2_join:
.LBB0_382:
	s_waitcnt vmcnt(0)
	v_add_u32_e32 v0, 0x11000, v140
	s_barrier
	v_add_u32_e32 v134, v0, v141
	v_add_u32_e32 v0, v0, v139
	ds_read_b128 v[130:133], v134 offset:4096
	ds_read_b128 v[138:141], v0
	ds_read_b128 v[142:145], v134 offset:5120
	ds_read_b128 v[146:149], v0 offset:1024
	ds_read_b128 v[150:153], v134 offset:6144
	ds_read_b128 v[154:157], v134 offset:7168
	ds_read_b128 v[158:161], v134 offset:8192
	ds_read_b128 v[162:165], v134 offset:9216
	ds_read_b128 v[166:169], v134 offset:10240
	ds_read_b128 v[170:173], v134 offset:11264
	ds_read_b128 v[174:177], v0 offset:2048
	ds_read_b128 v[178:181], v0 offset:3072
	s_waitcnt lgkmcnt(0)
	v_mfma_f32_16x16x32_bf16 v[98:101], v[130:133], v[138:141], v[98:101]
	v_and_b32_e32 v197, 63, v136
	v_ashrrev_i32_e32 v236, 6, v136
	v_mfma_f32_16x16x32_bf16 v[94:97], v[142:145], v[138:141], v[94:97]
	v_mfma_f32_16x16x32_bf16 v[90:93], v[150:153], v[138:141], v[90:93]
	v_mfma_f32_16x16x32_bf16 v[86:89], v[154:157], v[138:141], v[86:89]
	v_mfma_f32_16x16x32_bf16 v[82:85], v[158:161], v[138:141], v[82:85]
	v_mfma_f32_16x16x32_bf16 v[78:81], v[162:165], v[138:141], v[78:81]
	v_mfma_f32_16x16x32_bf16 v[74:77], v[166:169], v[138:141], v[74:77]
	v_mfma_f32_16x16x32_bf16 v[70:73], v[170:173], v[138:141], v[70:73]
	v_mfma_f32_16x16x32_bf16 v[126:129], v[130:133], v[146:149], v[126:129]
	v_mfma_f32_16x16x32_bf16 v[122:125], v[142:145], v[146:149], v[122:125]
	v_mfma_f32_16x16x32_bf16 v[118:121], v[150:153], v[146:149], v[118:121]
	v_mfma_f32_16x16x32_bf16 v[114:117], v[154:157], v[146:149], v[114:117]
	v_mfma_f32_16x16x32_bf16 v[110:113], v[158:161], v[146:149], v[110:113]
	v_mfma_f32_16x16x32_bf16 v[106:109], v[162:165], v[146:149], v[106:109]
	v_mfma_f32_16x16x32_bf16 v[102:105], v[166:169], v[146:149], v[102:105]
	v_mfma_f32_16x16x32_bf16 v[66:69], v[170:173], v[146:149], v[66:69]
	v_mfma_f32_16x16x32_bf16 v[34:37], v[130:133], v[174:177], v[34:37]
	v_mfma_f32_16x16x32_bf16 v[30:33], v[142:145], v[174:177], v[30:33]
	v_mfma_f32_16x16x32_bf16 v[26:29], v[150:153], v[174:177], v[26:29]
	v_mfma_f32_16x16x32_bf16 v[22:25], v[154:157], v[174:177], v[22:25]
	v_mfma_f32_16x16x32_bf16 v[18:21], v[158:161], v[174:177], v[18:21]
	v_mfma_f32_16x16x32_bf16 v[14:17], v[162:165], v[174:177], v[14:17]
	v_mfma_f32_16x16x32_bf16 v[10:13], v[166:169], v[174:177], v[10:13]
	v_mfma_f32_16x16x32_bf16 v[6:9], v[170:173], v[174:177], v[6:9]
	v_mfma_f32_16x16x32_bf16 v[62:65], v[130:133], v[178:181], v[62:65]
	v_mfma_f32_16x16x32_bf16 v[58:61], v[142:145], v[178:181], v[58:61]
	v_mfma_f32_16x16x32_bf16 v[54:57], v[150:153], v[178:181], v[54:57]
	v_mfma_f32_16x16x32_bf16 v[50:53], v[154:157], v[178:181], v[50:53]
	v_mfma_f32_16x16x32_bf16 v[46:49], v[158:161], v[178:181], v[46:49]
	v_mfma_f32_16x16x32_bf16 v[42:45], v[162:165], v[178:181], v[42:45]
	v_mfma_f32_16x16x32_bf16 v[38:41], v[166:169], v[178:181], v[38:41]
	v_mfma_f32_16x16x32_bf16 v[2:5], v[170:173], v[178:181], v[2:5]
	s_barrier
	s_not_b64 s[6:7], s[10:11]
	v_and_b32_e32 v138, 15, v212
	v_bfe_u32 v139, v212, 4, 2
	v_lshrrev_b32_e32 v140, 6, v212
	v_and_b32_e32 v141, 63, v212
	v_readfirstlane_b32 s90, v140
	v_and_b32_e32 v142, 0xff, v212
	v_lshlrev_b32_e32 v142, 4, v142
	s_cmp_lt_u32 s90, 4
	s_cselect_b32 s92, s14, s12
	s_cselect_b32 s93, s15, s13
	s_nop 3
	global_load_dwordx4 v[176:179], v142, s[92:93]
	v_lshlrev_b32_e32 v143, 4, v212
	v_add_u32_e32 v143, 0x20000, v143
	v_lshlrev_b32_e32 v134, 6, v138
	v_add_u32_e32 v135, 0x22000, v134
	v_lshl_add_u32 v134, v140, 3, v135
	v_lshlrev_b32_e32 v136, 9, v140
	v_lshl_add_u32 v136, v139, 4, v136
	v_add_u32_e32 v136, 0x20000, v136
	s_cmp_lg_u64 s[10:11], 0
	s_cbranch_scc1 .Le2_l1
	s_lshl_b32 s40, s48, 18
	s_lshl_b32 s91, s90, 13
	s_add_u32 s96, s52, s40
	s_addc_u32 s97, s53, 0
	s_add_u32 s96, s96, s91
	s_addc_u32 s97, s97, 0
	s_lshl_b32 s40, s90, 1
	v_xor_b32_e32 v208, s40, v141
	v_lshlrev_b32_e32 v208, 4, v208
	s_add_u32 s40, s40, 1
	v_xor_b32_e32 v209, s40, v141
	v_lshlrev_b32_e32 v209, 4, v209
	v_lshlrev_b32_e32 v133, 12, v138
	v_lshl_add_u32 v133, v140, 9, v133
	v_add_u32_e32 v200, 0, v139
	v_xor_b32_e32 v200, v200, v138
	v_lshl_add_u32 v200, v200, 4, v133
	v_add_u32_e32 v204, 0x10000, v200
	v_add_u32_e32 v201, 4, v139
	v_xor_b32_e32 v201, v201, v138
	v_lshl_add_u32 v201, v201, 4, v133
	v_add_u32_e32 v205, 0x10000, v201
	v_add_u32_e32 v202, 8, v139
	v_xor_b32_e32 v202, v202, v138
	v_lshl_add_u32 v202, v202, 4, v133
	v_add_u32_e32 v206, 0x10000, v202
	v_add_u32_e32 v203, 12, v139
	v_xor_b32_e32 v203, v203, v138
	v_lshl_add_u32 v203, v203, 4, v133
	v_add_u32_e32 v207, 0x10000, v203
	v_and_b32_e32 v137, 1, v139
	v_lshlrev_b32_e32 v137, 5, v137
	v_lshrrev_b32_e32 v130, 1, v139
	v_lshl_or_b32 v137, v130, 4, v137
	v_lshl_or_b32 v137, v138, 6, v137
	v_lshl_or_b32 v137, v140, 15, v137
	s_lshr_b32 s40, s48, 1
	s_lshl_b32 s40, s40, 18
	s_and_b32 s46, s48, 1
	s_lshl_b32 s46, s46, 12
	s_add_u32 s40, s40, s46
	s_add_u32 s78, s56, s40
	s_addc_u32 s79, s57, 0
	s_add_u32 s92, s96, 0x0
	s_addc_u32 s93, s97, 0
	s_add_u32 s40, s91, 0x0
	s_mov_b32 m0, s40
	s_nop 0
	global_load_lds_dwordx4 v208, s[92:93]
	global_load_lds_dwordx4 v208, s[92:93] offset:1024
	global_load_lds_dwordx4 v208, s[92:93] offset:2048
	global_load_lds_dwordx4 v208, s[92:93] offset:3072
	s_add_u32 s92, s96, 0x1000
	s_addc_u32 s93, s97, 0
	s_add_u32 s40, s91, 0x1000
	s_mov_b32 m0, s40
	s_nop 0
	global_load_lds_dwordx4 v209, s[92:93]
	global_load_lds_dwordx4 v209, s[92:93] offset:1024
	global_load_lds_dwordx4 v209, s[92:93] offset:2048
	global_load_lds_dwordx4 v209, s[92:93] offset:3072
	s_add_u32 s92, s96, 0x10000
	s_addc_u32 s93, s97, 0
	s_add_u32 s40, s91, 0x10000
	s_mov_b32 m0, s40
	s_nop 0
	global_load_lds_dwordx4 v208, s[92:93]
	global_load_lds_dwordx4 v208, s[92:93] offset:1024
	global_load_lds_dwordx4 v208, s[92:93] offset:2048
	global_load_lds_dwordx4 v208, s[92:93] offset:3072
	s_add_u32 s92, s96, 0x11000
	s_addc_u32 s93, s97, 0
	s_add_u32 s40, s91, 0x11000
	s_mov_b32 m0, s40
	s_nop 0
	global_load_lds_dwordx4 v209, s[92:93]
	global_load_lds_dwordx4 v209, s[92:93] offset:1024
	global_load_lds_dwordx4 v209, s[92:93] offset:2048
	global_load_lds_dwordx4 v209, s[92:93] offset:3072
	s_waitcnt vmcnt(16)
	ds_write_b128 v143, v[176:179]
	s_waitcnt vmcnt(8) lgkmcnt(0)
	s_barrier
; DI float bf2f(unsigned b) { return __uint_as_float(b << 16); }
; DI void unit_O(const Params& p, char* lds, int l, int tile, int glu_tiles, int tile_b) {
;     ...
;         float s2[2], ss2[2];
; #pragma unroll
;         for (int mh = 0; mh < 2; ++mh) {
;             const int mt = half * 2 + mh, rl = mh * 16 + l15;
;             float s = 0.f, ss = 0.f;
; #pragma unroll
;             for (int nt = 0; nt < 8; ++nt) {
;                 f32x4 xr;
;                 if (l == 0) {
;                     const int chunk = wid * 32 + nt * 4 + quad;
;                     xr = *(const f32x4*)(XR + rl * 4096 + ((chunk ^ l15) << 4));
;                 } else {
;                     const u32x2 hb = *(const u32x2*)(XR + ((wid * 4 + (nt >> 1)) * 32 + rl) * 64 + (nt & 1) * 32 + quad * 8);
;                     xr = (f32x4){bf2f(hb[0] & 0xffffu), bf2f(hb[0] >> 16), bf2f(hb[1] & 0xffffu), bf2f(hb[1] >> 16)};
;                 }
; #pragma unroll
;                 for (int i = 0; i < 4; ++i) { const float v = acc[mt][nt][i] + DN_ALPHA * xr[i]; acc[mt][nt][i] = v; s += v; ss += v * v; }
;             }
;             s2[mh] = s; ss2[mh] = ss;
;         }
; #pragma unroll
;         for (int mh = 0; mh < 2; ++mh) { s2[mh] += __shfl_xor(s2[mh], 16); ss2[mh] += __shfl_xor(ss2[mh], 16); }
; #pragma unroll
;         for (int mh = 0; mh < 2; ++mh) { s2[mh] += __shfl_xor(s2[mh], 32); ss2[mh] += __shfl_xor(ss2[mh], 32); }
;         if (quad == 0) {
; #pragma unroll
;             for (int mh = 0; mh < 2; ++mh) *(f32x2*)&red[((mh * 16 + l15) * 8 + wid) * 2] = (f32x2){s2[mh], ss2[mh]};
;         }
;         __syncthreads();
;         if (half == 0) issue_x(1);
; #pragma unroll
;         for (int mh = 0; mh < 2; ++mh) {
;             const int mt = half * 2 + mh, rl = mh * 16 + l15, row = mt * 16 + l15;
;             float s = 0.f, ss = 0.f;
; #pragma unroll
;             for (int w = 0; w < 4; ++w) { const f32x4 v = *(const f32x4*)&red[rl * 16 + 4 * w]; s += v[0] + v[2]; ss += v[1] + v[3]; }
;             const float mu = s * (1.f / 1024.f);
;             const float var = ss * (1.f / 1024.f) - mu * mu;
;             const float rs = rsqrtf(var + LN_EPS);
	ds_read_b128 v[144:147], v200
	ds_read_b128 v[148:151], v201
	ds_read_b128 v[152:155], v202
	ds_read_b128 v[156:159], v203
	ds_read_b128 v[160:163], v200 offset:256
	ds_read_b128 v[164:167], v201 offset:256
	ds_read_b128 v[168:171], v202 offset:256
	ds_read_b128 v[172:175], v203 offset:256
	s_waitcnt lgkmcnt(7)
	v_fmac_f32_e32 v98, s58, v144
	v_fmac_f32_e32 v99, s58, v145
	v_fmac_f32_e32 v100, s58, v146
	v_fmac_f32_e32 v101, s58, v147
	v_mov_b32_e32 v196, v98
	v_mul_f32_e32 v197, v98, v98
	v_mov_b32_e32 v130, v99
	v_mul_f32_e32 v142, v99, v99
	v_add_f32_e32 v196, v196, v100
	v_fmac_f32_e32 v197, v100, v100
	v_add_f32_e32 v130, v130, v101
	v_fmac_f32_e32 v142, v101, v101
	s_waitcnt lgkmcnt(6)
	v_fmac_f32_e32 v94, s58, v148
	v_fmac_f32_e32 v95, s58, v149
	v_fmac_f32_e32 v96, s58, v150
	v_fmac_f32_e32 v97, s58, v151
	v_add_f32_e32 v196, v196, v94
	v_fmac_f32_e32 v197, v94, v94
	v_add_f32_e32 v130, v130, v95
	v_fmac_f32_e32 v142, v95, v95
	v_add_f32_e32 v196, v196, v96
	v_fmac_f32_e32 v197, v96, v96
	v_add_f32_e32 v130, v130, v97
	v_fmac_f32_e32 v142, v97, v97
	s_waitcnt lgkmcnt(5)
	v_fmac_f32_e32 v90, s58, v152
	v_fmac_f32_e32 v91, s58, v153
	v_fmac_f32_e32 v92, s58, v154
	v_fmac_f32_e32 v93, s58, v155
	v_add_f32_e32 v196, v196, v90
	v_fmac_f32_e32 v197, v90, v90
	v_add_f32_e32 v130, v130, v91
	v_fmac_f32_e32 v142, v91, v91
	v_add_f32_e32 v196, v196, v92
	v_fmac_f32_e32 v197, v92, v92
	v_add_f32_e32 v130, v130, v93
	v_fmac_f32_e32 v142, v93, v93
	s_waitcnt lgkmcnt(4)
	v_fmac_f32_e32 v86, s58, v156
	v_fmac_f32_e32 v87, s58, v157
	v_fmac_f32_e32 v88, s58, v158
	v_fmac_f32_e32 v89, s58, v159
	v_add_f32_e32 v196, v196, v86
	v_fmac_f32_e32 v197, v86, v86
	v_add_f32_e32 v130, v130, v87
	v_fmac_f32_e32 v142, v87, v87
	v_add_f32_e32 v196, v196, v88
	v_fmac_f32_e32 v197, v88, v88
	v_add_f32_e32 v130, v130, v89
	v_fmac_f32_e32 v142, v89, v89
	s_waitcnt lgkmcnt(3)
	v_fmac_f32_e32 v82, s58, v160
	v_fmac_f32_e32 v83, s58, v161
	v_fmac_f32_e32 v84, s58, v162
	v_fmac_f32_e32 v85, s58, v163
	v_add_f32_e32 v196, v196, v82
	v_fmac_f32_e32 v197, v82, v82
	v_add_f32_e32 v130, v130, v83
	v_fmac_f32_e32 v142, v83, v83
	v_add_f32_e32 v196, v196, v84
	v_fmac_f32_e32 v197, v84, v84
	v_add_f32_e32 v130, v130, v85
	v_fmac_f32_e32 v142, v85, v85
	s_waitcnt lgkmcnt(2)
	v_fmac_f32_e32 v78, s58, v164
	v_fmac_f32_e32 v79, s58, v165
	v_fmac_f32_e32 v80, s58, v166
	v_fmac_f32_e32 v81, s58, v167
	v_add_f32_e32 v196, v196, v78
	v_fmac_f32_e32 v197, v78, v78
	v_add_f32_e32 v130, v130, v79
	v_fmac_f32_e32 v142, v79, v79
	v_add_f32_e32 v196, v196, v80
	v_fmac_f32_e32 v197, v80, v80
	v_add_f32_e32 v130, v130, v81
	v_fmac_f32_e32 v142, v81, v81
	s_waitcnt lgkmcnt(1)
	v_fmac_f32_e32 v74, s58, v168
	v_fmac_f32_e32 v75, s58, v169
	v_fmac_f32_e32 v76, s58, v170
	v_fmac_f32_e32 v77, s58, v171
	v_add_f32_e32 v196, v196, v74
	v_fmac_f32_e32 v197, v74, v74
	v_add_f32_e32 v130, v130, v75
	v_fmac_f32_e32 v142, v75, v75
	v_add_f32_e32 v196, v196, v76
	v_fmac_f32_e32 v197, v76, v76
	v_add_f32_e32 v130, v130, v77
	v_fmac_f32_e32 v142, v77, v77
	s_waitcnt lgkmcnt(0)
	v_fmac_f32_e32 v70, s58, v172
	v_fmac_f32_e32 v71, s58, v173
	v_fmac_f32_e32 v72, s58, v174
	v_fmac_f32_e32 v73, s58, v175
	v_add_f32_e32 v196, v196, v70
	v_fmac_f32_e32 v197, v70, v70
	v_add_f32_e32 v130, v130, v71
	v_fmac_f32_e32 v142, v71, v71
	v_add_f32_e32 v196, v196, v72
	v_fmac_f32_e32 v197, v72, v72
	v_add_f32_e32 v130, v130, v73
	v_fmac_f32_e32 v142, v73, v73
	v_add_f32_e32 v196, v196, v130
	v_add_f32_e32 v197, v197, v142
	v_mov_b32_e32 v198, v196
	v_mov_b32_e32 v199, v197
	s_nop 1
	v_permlane16_swap_b32 v198, v196
	v_permlane16_swap_b32 v199, v197
	v_add_f32_e32 v196, v196, v198
	v_add_f32_e32 v197, v197, v199
	v_mov_b32_e32 v198, v196
	v_mov_b32_e32 v199, v197
	s_nop 1
	v_permlane32_swap_b32 v198, v196
	v_permlane32_swap_b32 v199, v197
	v_add_f32_e32 v196, v196, v198
	v_add_f32_e32 v197, v197, v199
	s_mov_b64 exec, 0xffff
	ds_write_b64 v134, v[196:197]
	s_mov_b64 exec, -1
	s_waitcnt lgkmcnt(0)
	s_barrier
	s_add_u32 s92, s96, 0x20000
	s_addc_u32 s93, s97, 0
	s_add_u32 s40, s91, 0x0
	s_mov_b32 m0, s40
	s_nop 0
	global_load_lds_dwordx4 v208, s[92:93]
	global_load_lds_dwordx4 v208, s[92:93] offset:1024
	global_load_lds_dwordx4 v208, s[92:93] offset:2048
	global_load_lds_dwordx4 v208, s[92:93] offset:3072
	s_add_u32 s92, s96, 0x21000
	s_addc_u32 s93, s97, 0
	s_add_u32 s40, s91, 0x1000
	s_mov_b32 m0, s40
	s_nop 0
	global_load_lds_dwordx4 v209, s[92:93]
	global_load_lds_dwordx4 v209, s[92:93] offset:1024
	global_load_lds_dwordx4 v209, s[92:93] offset:2048
	global_load_lds_dwordx4 v209, s[92:93] offset:3072
	ds_read_b128 v[160:163], v135 offset:0
	ds_read_b128 v[164:167], v135 offset:16
	ds_read_b128 v[168:171], v135 offset:32
	ds_read_b128 v[172:175], v135 offset:48
	s_waitcnt lgkmcnt(0)
	v_add_f32_e32 v160, v160, v162
	v_add_f32_e32 v161, v161, v163
	v_add_f32_e32 v164, v164, v166
	v_add_f32_e32 v165, v165, v167
	v_add_f32_e32 v168, v168, v170
	v_add_f32_e32 v169, v169, v171
	v_add_f32_e32 v172, v172, v174
	v_add_f32_e32 v173, v173, v175
	v_add_f32_e32 v160, v160, v164
	v_add_f32_e32 v161, v161, v165
	v_add_f32_e32 v168, v168, v172
	v_add_f32_e32 v169, v169, v173
	v_add_f32_e32 v160, v160, v168
	v_add_f32_e32 v161, v161, v169
	v_mul_f32_e32 v192, 0x3a800000, v160
	v_mul_f32_e32 v193, 0x3a800000, v161
	v_fma_f32 v193, -v192, v192, v193
	v_add_f32_e32 v193, 0x3727c5ac, v193
	v_rsq_f32_e32 v193, v193
	s_nop 0
	s_add_u32 s94, s78, 0x0
	s_addc_u32 s95, s79, 0
	ds_read_b128 v[176:179], v136
	ds_read_b128 v[180:183], v136 offset:4096
	ds_read_b128 v[184:187], v136 offset:64
	ds_read_b128 v[188:191], v136 offset:4160
	s_waitcnt lgkmcnt(2)
; DI unsigned pk2(float lo, float hi) { const f32x2 v = {lo, hi}; const bf16x2_t b = __builtin_convertvector(v, bf16x2_t); return __builtin_bit_cast(unsigned, b); }
; DI size_t xb_off(int tok, int col) { return ((size_t)(((tok >> 7) * 32 + (col >> 5)) * 128 + (tok & 127))) * 32 + (col & 31); }
; DI void unit_O(const Params& p, char* lds, int l, int tile, int glu_tiles, int tile_b) {
;     ...
;             float* orow = xo + (r0 + row) * 1024 + wid * 128 + quad * 4;
;             bf16_t* brow = xbo + xb_off((int)r0 + row, wid * 128) + quad * 4;
;             const float* gp = GB + wid * 128 + quad * 4;
; #pragma unroll
;             for (int nt = 0; nt < 8; ++nt) {
;                 const f32x4 g = *(const f32x4*)(gp + nt * 16), bb = *(const f32x4*)(gp + 1024 + nt * 16);
;                 f32x4 o;
; #pragma unroll
;                 for (int i = 0; i < 4; ++i) o[i] = (acc[mt][nt][i] - mu) * rs * g[i] + bb[i];
;                 if (l == 0) *(u32x2*)(brow + (nt >> 1) * 4096 + (nt & 1) * 16) = (u32x2){pk2(o[0], o[1]), pk2(o[2], o[3])};
;                 else *(f32x4*)(orow + nt * 16) = o;
;             }
;         }
	v_sub_f32_e32 v98, v98, v192
	v_mul_f32_e32 v98, v98, v193
	v_fma_f32 v98, v176, v98, v180
	v_sub_f32_e32 v99, v99, v192
	v_mul_f32_e32 v99, v99, v193
	v_fma_f32 v99, v177, v99, v181
	v_sub_f32_e32 v100, v100, v192
	v_mul_f32_e32 v100, v100, v193
	v_fma_f32 v100, v178, v100, v182
	v_sub_f32_e32 v101, v101, v192
	v_mul_f32_e32 v101, v101, v193
	v_fma_f32 v101, v179, v101, v183
	v_cvt_pk_bf16_f32 v144, v98, v99
	v_cvt_pk_bf16_f32 v145, v100, v101
	ds_read_b128 v[176:179], v136 offset:128
	ds_read_b128 v[180:183], v136 offset:4224
	s_waitcnt lgkmcnt(2)
	v_sub_f32_e32 v94, v94, v192
	v_mul_f32_e32 v94, v94, v193
	v_fma_f32 v94, v184, v94, v188
	v_sub_f32_e32 v95, v95, v192
	v_mul_f32_e32 v95, v95, v193
	v_fma_f32 v95, v185, v95, v189
	v_sub_f32_e32 v96, v96, v192
	v_mul_f32_e32 v96, v96, v193
	v_fma_f32 v96, v186, v96, v190
	v_sub_f32_e32 v97, v97, v192
	v_mul_f32_e32 v97, v97, v193
	v_fma_f32 v97, v187, v97, v191
	v_cvt_pk_bf16_f32 v146, v94, v95
	v_cvt_pk_bf16_f32 v147, v96, v97
	s_nop 1
	v_permlane16_swap_b32 v144, v146
	v_permlane16_swap_b32 v145, v147
	global_store_dwordx4 v137, v[144:147], s[94:95] sc1
	s_add_u32 s94, s94, 0x2000
	s_addc_u32 s95, s95, 0
	ds_read_b128 v[184:187], v136 offset:192
	ds_read_b128 v[188:191], v136 offset:4288
	s_waitcnt lgkmcnt(2)
	v_sub_f32_e32 v90, v90, v192
	v_mul_f32_e32 v90, v90, v193
	v_fma_f32 v90, v176, v90, v180
	v_sub_f32_e32 v91, v91, v192
	v_mul_f32_e32 v91, v91, v193
	v_fma_f32 v91, v177, v91, v181
	v_sub_f32_e32 v92, v92, v192
	v_mul_f32_e32 v92, v92, v193
	v_fma_f32 v92, v178, v92, v182
	v_sub_f32_e32 v93, v93, v192
	v_mul_f32_e32 v93, v93, v193
	v_fma_f32 v93, v179, v93, v183
	v_cvt_pk_bf16_f32 v152, v90, v91
	v_cvt_pk_bf16_f32 v153, v92, v93
	ds_read_b128 v[176:179], v136 offset:256
	ds_read_b128 v[180:183], v136 offset:4352
	s_waitcnt lgkmcnt(2)
	v_sub_f32_e32 v86, v86, v192
	v_mul_f32_e32 v86, v86, v193
	v_fma_f32 v86, v184, v86, v188
	v_sub_f32_e32 v87, v87, v192
	v_mul_f32_e32 v87, v87, v193
	v_fma_f32 v87, v185, v87, v189
	v_sub_f32_e32 v88, v88, v192
	v_mul_f32_e32 v88, v88, v193
	v_fma_f32 v88, v186, v88, v190
	v_sub_f32_e32 v89, v89, v192
	v_mul_f32_e32 v89, v89, v193
	v_fma_f32 v89, v187, v89, v191
	v_cvt_pk_bf16_f32 v154, v86, v87
	v_cvt_pk_bf16_f32 v155, v88, v89
	s_nop 1
	v_permlane16_swap_b32 v152, v154
	v_permlane16_swap_b32 v153, v155
	global_store_dwordx4 v137, v[152:155], s[94:95] sc1
	s_add_u32 s94, s94, 0x2000
	s_addc_u32 s95, s95, 0
	ds_read_b128 v[184:187], v136 offset:320
	ds_read_b128 v[188:191], v136 offset:4416
	s_waitcnt lgkmcnt(2)
	v_sub_f32_e32 v82, v82, v192
	v_mul_f32_e32 v82, v82, v193
	v_fma_f32 v82, v176, v82, v180
	v_sub_f32_e32 v83, v83, v192
	v_mul_f32_e32 v83, v83, v193
	v_fma_f32 v83, v177, v83, v181
	v_sub_f32_e32 v84, v84, v192
	v_mul_f32_e32 v84, v84, v193
	v_fma_f32 v84, v178, v84, v182
	v_sub_f32_e32 v85, v85, v192
	v_mul_f32_e32 v85, v85, v193
	v_fma_f32 v85, v179, v85, v183
	v_cvt_pk_bf16_f32 v144, v82, v83
	v_cvt_pk_bf16_f32 v145, v84, v85
	ds_read_b128 v[176:179], v136 offset:384
	ds_read_b128 v[180:183], v136 offset:4480
	s_waitcnt lgkmcnt(2)
	v_sub_f32_e32 v78, v78, v192
	v_mul_f32_e32 v78, v78, v193
	v_fma_f32 v78, v184, v78, v188
	v_sub_f32_e32 v79, v79, v192
	v_mul_f32_e32 v79, v79, v193
	v_fma_f32 v79, v185, v79, v189
	v_sub_f32_e32 v80, v80, v192
	v_mul_f32_e32 v80, v80, v193
	v_fma_f32 v80, v186, v80, v190
	v_sub_f32_e32 v81, v81, v192
	v_mul_f32_e32 v81, v81, v193
	v_fma_f32 v81, v187, v81, v191
	v_cvt_pk_bf16_f32 v146, v78, v79
	v_cvt_pk_bf16_f32 v147, v80, v81
	s_nop 1
	v_permlane16_swap_b32 v144, v146
	v_permlane16_swap_b32 v145, v147
	global_store_dwordx4 v137, v[144:147], s[94:95] sc1
	s_add_u32 s94, s94, 0x2000
	s_addc_u32 s95, s95, 0
	ds_read_b128 v[184:187], v136 offset:448
	ds_read_b128 v[188:191], v136 offset:4544
	s_waitcnt lgkmcnt(2)
	v_sub_f32_e32 v74, v74, v192
	v_mul_f32_e32 v74, v74, v193
	v_fma_f32 v74, v176, v74, v180
	v_sub_f32_e32 v75, v75, v192
	v_mul_f32_e32 v75, v75, v193
	v_fma_f32 v75, v177, v75, v181
	v_sub_f32_e32 v76, v76, v192
	v_mul_f32_e32 v76, v76, v193
	v_fma_f32 v76, v178, v76, v182
	v_sub_f32_e32 v77, v77, v192
	v_mul_f32_e32 v77, v77, v193
	v_fma_f32 v77, v179, v77, v183
	v_cvt_pk_bf16_f32 v152, v74, v75
	v_cvt_pk_bf16_f32 v153, v76, v77
	s_waitcnt lgkmcnt(0)
	v_sub_f32_e32 v70, v70, v192
	v_mul_f32_e32 v70, v70, v193
	v_fma_f32 v70, v184, v70, v188
	v_sub_f32_e32 v71, v71, v192
	v_mul_f32_e32 v71, v71, v193
	v_fma_f32 v71, v185, v71, v189
	v_sub_f32_e32 v72, v72, v192
	v_mul_f32_e32 v72, v72, v193
	v_fma_f32 v72, v186, v72, v190
	v_sub_f32_e32 v73, v73, v192
	v_mul_f32_e32 v73, v73, v193
	v_fma_f32 v73, v187, v73, v191
	v_cvt_pk_bf16_f32 v154, v70, v71
	v_cvt_pk_bf16_f32 v155, v72, v73
	s_nop 1
	v_permlane16_swap_b32 v152, v154
	v_permlane16_swap_b32 v153, v155
	global_store_dwordx4 v137, v[152:155], s[94:95] sc1
	s_waitcnt vmcnt(12) lgkmcnt(0)
	s_barrier
; DI float bf2f(unsigned b) { return __uint_as_float(b << 16); }
; DI void unit_O(const Params& p, char* lds, int l, int tile, int glu_tiles, int tile_b) {
;     ...
;         float s2[2], ss2[2];
; #pragma unroll
;         for (int mh = 0; mh < 2; ++mh) {
;             const int mt = half * 2 + mh, rl = mh * 16 + l15;
;             float s = 0.f, ss = 0.f;
; #pragma unroll
;             for (int nt = 0; nt < 8; ++nt) {
;                 f32x4 xr;
;                 if (l == 0) {
;                     const int chunk = wid * 32 + nt * 4 + quad;
;                     xr = *(const f32x4*)(XR + rl * 4096 + ((chunk ^ l15) << 4));
;                 } else {
;                     const u32x2 hb = *(const u32x2*)(XR + ((wid * 4 + (nt >> 1)) * 32 + rl) * 64 + (nt & 1) * 32 + quad * 8);
;                     xr = (f32x4){bf2f(hb[0] & 0xffffu), bf2f(hb[0] >> 16), bf2f(hb[1] & 0xffffu), bf2f(hb[1] >> 16)};
;                 }
; #pragma unroll
;                 for (int i = 0; i < 4; ++i) { const float v = acc[mt][nt][i] + DN_ALPHA * xr[i]; acc[mt][nt][i] = v; s += v; ss += v * v; }
;             }
;             s2[mh] = s; ss2[mh] = ss;
;         }
; #pragma unroll
;         for (int mh = 0; mh < 2; ++mh) { s2[mh] += __shfl_xor(s2[mh], 16); ss2[mh] += __shfl_xor(ss2[mh], 16); }
; #pragma unroll
;         for (int mh = 0; mh < 2; ++mh) { s2[mh] += __shfl_xor(s2[mh], 32); ss2[mh] += __shfl_xor(ss2[mh], 32); }
;         if (quad == 0) {
; #pragma unroll
;             for (int mh = 0; mh < 2; ++mh) *(f32x2*)&red[((mh * 16 + l15) * 8 + wid) * 2] = (f32x2){s2[mh], ss2[mh]};
;         }
;         __syncthreads();
;         if (half == 0) issue_x(1);
; #pragma unroll
;         for (int mh = 0; mh < 2; ++mh) {
;             const int mt = half * 2 + mh, rl = mh * 16 + l15, row = mt * 16 + l15;
;             float s = 0.f, ss = 0.f;
; #pragma unroll
;             for (int w = 0; w < 4; ++w) { const f32x4 v = *(const f32x4*)&red[rl * 16 + 4 * w]; s += v[0] + v[2]; ss += v[1] + v[3]; }
;             const float mu = s * (1.f / 1024.f);
;             const float var = ss * (1.f / 1024.f) - mu * mu;
;             const float rs = rsqrtf(var + LN_EPS);
	ds_read_b128 v[144:147], v204
	ds_read_b128 v[148:151], v205
	ds_read_b128 v[152:155], v206
	ds_read_b128 v[156:159], v207
	ds_read_b128 v[160:163], v204 offset:256
	ds_read_b128 v[164:167], v205 offset:256
	ds_read_b128 v[168:171], v206 offset:256
	ds_read_b128 v[172:175], v207 offset:256
	s_waitcnt lgkmcnt(7)
	v_fmac_f32_e32 v126, s58, v144
	v_fmac_f32_e32 v127, s58, v145
	v_fmac_f32_e32 v128, s58, v146
	v_fmac_f32_e32 v129, s58, v147
	v_mov_b32_e32 v196, v126
	v_mul_f32_e32 v197, v126, v126
	v_mov_b32_e32 v130, v127
	v_mul_f32_e32 v142, v127, v127
	v_add_f32_e32 v196, v196, v128
	v_fmac_f32_e32 v197, v128, v128
	v_add_f32_e32 v130, v130, v129
	v_fmac_f32_e32 v142, v129, v129
	s_waitcnt lgkmcnt(6)
	v_fmac_f32_e32 v122, s58, v148
	v_fmac_f32_e32 v123, s58, v149
	v_fmac_f32_e32 v124, s58, v150
	v_fmac_f32_e32 v125, s58, v151
	v_add_f32_e32 v196, v196, v122
	v_fmac_f32_e32 v197, v122, v122
	v_add_f32_e32 v130, v130, v123
	v_fmac_f32_e32 v142, v123, v123
	v_add_f32_e32 v196, v196, v124
	v_fmac_f32_e32 v197, v124, v124
	v_add_f32_e32 v130, v130, v125
	v_fmac_f32_e32 v142, v125, v125
	s_waitcnt lgkmcnt(5)
	v_fmac_f32_e32 v118, s58, v152
	v_fmac_f32_e32 v119, s58, v153
	v_fmac_f32_e32 v120, s58, v154
	v_fmac_f32_e32 v121, s58, v155
	v_add_f32_e32 v196, v196, v118
	v_fmac_f32_e32 v197, v118, v118
	v_add_f32_e32 v130, v130, v119
	v_fmac_f32_e32 v142, v119, v119
	v_add_f32_e32 v196, v196, v120
	v_fmac_f32_e32 v197, v120, v120
	v_add_f32_e32 v130, v130, v121
	v_fmac_f32_e32 v142, v121, v121
	s_waitcnt lgkmcnt(4)
	v_fmac_f32_e32 v114, s58, v156
	v_fmac_f32_e32 v115, s58, v157
	v_fmac_f32_e32 v116, s58, v158
	v_fmac_f32_e32 v117, s58, v159
	v_add_f32_e32 v196, v196, v114
	v_fmac_f32_e32 v197, v114, v114
	v_add_f32_e32 v130, v130, v115
	v_fmac_f32_e32 v142, v115, v115
	v_add_f32_e32 v196, v196, v116
	v_fmac_f32_e32 v197, v116, v116
	v_add_f32_e32 v130, v130, v117
	v_fmac_f32_e32 v142, v117, v117
	s_waitcnt lgkmcnt(3)
	v_fmac_f32_e32 v110, s58, v160
	v_fmac_f32_e32 v111, s58, v161
	v_fmac_f32_e32 v112, s58, v162
	v_fmac_f32_e32 v113, s58, v163
	v_add_f32_e32 v196, v196, v110
	v_fmac_f32_e32 v197, v110, v110
	v_add_f32_e32 v130, v130, v111
	v_fmac_f32_e32 v142, v111, v111
	v_add_f32_e32 v196, v196, v112
	v_fmac_f32_e32 v197, v112, v112
	v_add_f32_e32 v130, v130, v113
	v_fmac_f32_e32 v142, v113, v113
	s_waitcnt lgkmcnt(2)
	v_fmac_f32_e32 v106, s58, v164
	v_fmac_f32_e32 v107, s58, v165
	v_fmac_f32_e32 v108, s58, v166
	v_fmac_f32_e32 v109, s58, v167
	v_add_f32_e32 v196, v196, v106
	v_fmac_f32_e32 v197, v106, v106
	v_add_f32_e32 v130, v130, v107
	v_fmac_f32_e32 v142, v107, v107
	v_add_f32_e32 v196, v196, v108
	v_fmac_f32_e32 v197, v108, v108
	v_add_f32_e32 v130, v130, v109
	v_fmac_f32_e32 v142, v109, v109
	s_waitcnt lgkmcnt(1)
	v_fmac_f32_e32 v102, s58, v168
	v_fmac_f32_e32 v103, s58, v169
	v_fmac_f32_e32 v104, s58, v170
	v_fmac_f32_e32 v105, s58, v171
	v_add_f32_e32 v196, v196, v102
	v_fmac_f32_e32 v197, v102, v102
	v_add_f32_e32 v130, v130, v103
	v_fmac_f32_e32 v142, v103, v103
	v_add_f32_e32 v196, v196, v104
	v_fmac_f32_e32 v197, v104, v104
	v_add_f32_e32 v130, v130, v105
	v_fmac_f32_e32 v142, v105, v105
	s_waitcnt lgkmcnt(0)
	v_fmac_f32_e32 v66, s58, v172
	v_fmac_f32_e32 v67, s58, v173
	v_fmac_f32_e32 v68, s58, v174
	v_fmac_f32_e32 v69, s58, v175
	v_add_f32_e32 v196, v196, v66
	v_fmac_f32_e32 v197, v66, v66
	v_add_f32_e32 v130, v130, v67
	v_fmac_f32_e32 v142, v67, v67
	v_add_f32_e32 v196, v196, v68
	v_fmac_f32_e32 v197, v68, v68
	v_add_f32_e32 v130, v130, v69
	v_fmac_f32_e32 v142, v69, v69
	v_add_f32_e32 v196, v196, v130
	v_add_f32_e32 v197, v197, v142
	v_mov_b32_e32 v198, v196
	v_mov_b32_e32 v199, v197
	s_nop 1
	v_permlane16_swap_b32 v198, v196
	v_permlane16_swap_b32 v199, v197
	v_add_f32_e32 v196, v196, v198
	v_add_f32_e32 v197, v197, v199
	v_mov_b32_e32 v198, v196
	v_mov_b32_e32 v199, v197
	s_nop 1
	v_permlane32_swap_b32 v198, v196
	v_permlane32_swap_b32 v199, v197
	v_add_f32_e32 v196, v196, v198
	v_add_f32_e32 v197, v197, v199
	s_mov_b64 exec, 0xffff
	ds_write_b64 v134, v[196:197]
	s_mov_b64 exec, -1
	s_waitcnt lgkmcnt(0)
	s_barrier
	s_add_u32 s92, s96, 0x30000
	s_addc_u32 s93, s97, 0
	s_add_u32 s40, s91, 0x10000
	s_mov_b32 m0, s40
	s_nop 0
	global_load_lds_dwordx4 v208, s[92:93]
	global_load_lds_dwordx4 v208, s[92:93] offset:1024
	global_load_lds_dwordx4 v208, s[92:93] offset:2048
	global_load_lds_dwordx4 v208, s[92:93] offset:3072
	s_add_u32 s92, s96, 0x31000
	s_addc_u32 s93, s97, 0
	s_add_u32 s40, s91, 0x11000
	s_mov_b32 m0, s40
	s_nop 0
	global_load_lds_dwordx4 v209, s[92:93]
	global_load_lds_dwordx4 v209, s[92:93] offset:1024
	global_load_lds_dwordx4 v209, s[92:93] offset:2048
	global_load_lds_dwordx4 v209, s[92:93] offset:3072
	ds_read_b128 v[160:163], v135 offset:0
	ds_read_b128 v[164:167], v135 offset:16
	ds_read_b128 v[168:171], v135 offset:32
	ds_read_b128 v[172:175], v135 offset:48
	s_waitcnt lgkmcnt(0)
	v_add_f32_e32 v160, v160, v162
	v_add_f32_e32 v161, v161, v163
	v_add_f32_e32 v164, v164, v166
	v_add_f32_e32 v165, v165, v167
	v_add_f32_e32 v168, v168, v170
	v_add_f32_e32 v169, v169, v171
	v_add_f32_e32 v172, v172, v174
	v_add_f32_e32 v173, v173, v175
	v_add_f32_e32 v160, v160, v164
	v_add_f32_e32 v161, v161, v165
	v_add_f32_e32 v168, v168, v172
	v_add_f32_e32 v169, v169, v173
	v_add_f32_e32 v160, v160, v168
	v_add_f32_e32 v161, v161, v169
	v_mul_f32_e32 v192, 0x3a800000, v160
	v_mul_f32_e32 v193, 0x3a800000, v161
	v_fma_f32 v193, -v192, v192, v193
	v_add_f32_e32 v193, 0x3727c5ac, v193
	v_rsq_f32_e32 v193, v193
	s_nop 0
	s_add_u32 s94, s78, 0x400
	s_addc_u32 s95, s79, 0
	ds_read_b128 v[176:179], v136
	ds_read_b128 v[180:183], v136 offset:4096
	ds_read_b128 v[184:187], v136 offset:64
	ds_read_b128 v[188:191], v136 offset:4160
	s_waitcnt lgkmcnt(2)
; DI unsigned pk2(float lo, float hi) { const f32x2 v = {lo, hi}; const bf16x2_t b = __builtin_convertvector(v, bf16x2_t); return __builtin_bit_cast(unsigned, b); }
; DI size_t xb_off(int tok, int col) { return ((size_t)(((tok >> 7) * 32 + (col >> 5)) * 128 + (tok & 127))) * 32 + (col & 31); }
; DI void unit_O(const Params& p, char* lds, int l, int tile, int glu_tiles, int tile_b) {
;     ...
;             float* orow = xo + (r0 + row) * 1024 + wid * 128 + quad * 4;
;             bf16_t* brow = xbo + xb_off((int)r0 + row, wid * 128) + quad * 4;
;             const float* gp = GB + wid * 128 + quad * 4;
; #pragma unroll
;             for (int nt = 0; nt < 8; ++nt) {
;                 const f32x4 g = *(const f32x4*)(gp + nt * 16), bb = *(const f32x4*)(gp + 1024 + nt * 16);
;                 f32x4 o;
; #pragma unroll
;                 for (int i = 0; i < 4; ++i) o[i] = (acc[mt][nt][i] - mu) * rs * g[i] + bb[i];
;                 if (l == 0) *(u32x2*)(brow + (nt >> 1) * 4096 + (nt & 1) * 16) = (u32x2){pk2(o[0], o[1]), pk2(o[2], o[3])};
;                 else *(f32x4*)(orow + nt * 16) = o;
;             }
;         }
	v_sub_f32_e32 v126, v126, v192
	v_mul_f32_e32 v126, v126, v193
	v_fma_f32 v126, v176, v126, v180
	v_sub_f32_e32 v127, v127, v192
	v_mul_f32_e32 v127, v127, v193
	v_fma_f32 v127, v177, v127, v181
	v_sub_f32_e32 v128, v128, v192
	v_mul_f32_e32 v128, v128, v193
	v_fma_f32 v128, v178, v128, v182
	v_sub_f32_e32 v129, v129, v192
	v_mul_f32_e32 v129, v129, v193
	v_fma_f32 v129, v179, v129, v183
	v_cvt_pk_bf16_f32 v144, v126, v127
	v_cvt_pk_bf16_f32 v145, v128, v129
	ds_read_b128 v[176:179], v136 offset:128
	ds_read_b128 v[180:183], v136 offset:4224
	s_waitcnt lgkmcnt(2)
	v_sub_f32_e32 v122, v122, v192
	v_mul_f32_e32 v122, v122, v193
	v_fma_f32 v122, v184, v122, v188
	v_sub_f32_e32 v123, v123, v192
	v_mul_f32_e32 v123, v123, v193
	v_fma_f32 v123, v185, v123, v189
	v_sub_f32_e32 v124, v124, v192
	v_mul_f32_e32 v124, v124, v193
	v_fma_f32 v124, v186, v124, v190
	v_sub_f32_e32 v125, v125, v192
	v_mul_f32_e32 v125, v125, v193
	v_fma_f32 v125, v187, v125, v191
	v_cvt_pk_bf16_f32 v146, v122, v123
	v_cvt_pk_bf16_f32 v147, v124, v125
	s_nop 1
	v_permlane16_swap_b32 v144, v146
	v_permlane16_swap_b32 v145, v147
	global_store_dwordx4 v137, v[144:147], s[94:95] sc1
	s_add_u32 s94, s94, 0x2000
	s_addc_u32 s95, s95, 0
	ds_read_b128 v[184:187], v136 offset:192
	ds_read_b128 v[188:191], v136 offset:4288
	s_waitcnt lgkmcnt(2)
	v_sub_f32_e32 v118, v118, v192
	v_mul_f32_e32 v118, v118, v193
	v_fma_f32 v118, v176, v118, v180
	v_sub_f32_e32 v119, v119, v192
	v_mul_f32_e32 v119, v119, v193
	v_fma_f32 v119, v177, v119, v181
	v_sub_f32_e32 v120, v120, v192
	v_mul_f32_e32 v120, v120, v193
	v_fma_f32 v120, v178, v120, v182
	v_sub_f32_e32 v121, v121, v192
	v_mul_f32_e32 v121, v121, v193
	v_fma_f32 v121, v179, v121, v183
	v_cvt_pk_bf16_f32 v152, v118, v119
	v_cvt_pk_bf16_f32 v153, v120, v121
	ds_read_b128 v[176:179], v136 offset:256
	ds_read_b128 v[180:183], v136 offset:4352
	s_waitcnt lgkmcnt(2)
	v_sub_f32_e32 v114, v114, v192
	v_mul_f32_e32 v114, v114, v193
	v_fma_f32 v114, v184, v114, v188
	v_sub_f32_e32 v115, v115, v192
	v_mul_f32_e32 v115, v115, v193
	v_fma_f32 v115, v185, v115, v189
	v_sub_f32_e32 v116, v116, v192
	v_mul_f32_e32 v116, v116, v193
	v_fma_f32 v116, v186, v116, v190
	v_sub_f32_e32 v117, v117, v192
	v_mul_f32_e32 v117, v117, v193
	v_fma_f32 v117, v187, v117, v191
	v_cvt_pk_bf16_f32 v154, v114, v115
	v_cvt_pk_bf16_f32 v155, v116, v117
	s_nop 1
	v_permlane16_swap_b32 v152, v154
	v_permlane16_swap_b32 v153, v155
	global_store_dwordx4 v137, v[152:155], s[94:95] sc1
	s_add_u32 s94, s94, 0x2000
	s_addc_u32 s95, s95, 0
	ds_read_b128 v[184:187], v136 offset:320
	ds_read_b128 v[188:191], v136 offset:4416
	s_waitcnt lgkmcnt(2)
	v_sub_f32_e32 v110, v110, v192
	v_mul_f32_e32 v110, v110, v193
	v_fma_f32 v110, v176, v110, v180
	v_sub_f32_e32 v111, v111, v192
	v_mul_f32_e32 v111, v111, v193
	v_fma_f32 v111, v177, v111, v181
	v_sub_f32_e32 v112, v112, v192
	v_mul_f32_e32 v112, v112, v193
	v_fma_f32 v112, v178, v112, v182
	v_sub_f32_e32 v113, v113, v192
	v_mul_f32_e32 v113, v113, v193
	v_fma_f32 v113, v179, v113, v183
	v_cvt_pk_bf16_f32 v144, v110, v111
	v_cvt_pk_bf16_f32 v145, v112, v113
	ds_read_b128 v[176:179], v136 offset:384
	ds_read_b128 v[180:183], v136 offset:4480
	s_waitcnt lgkmcnt(2)
	v_sub_f32_e32 v106, v106, v192
	v_mul_f32_e32 v106, v106, v193
	v_fma_f32 v106, v184, v106, v188
	v_sub_f32_e32 v107, v107, v192
	v_mul_f32_e32 v107, v107, v193
	v_fma_f32 v107, v185, v107, v189
	v_sub_f32_e32 v108, v108, v192
	v_mul_f32_e32 v108, v108, v193
	v_fma_f32 v108, v186, v108, v190
	v_sub_f32_e32 v109, v109, v192
	v_mul_f32_e32 v109, v109, v193
	v_fma_f32 v109, v187, v109, v191
	v_cvt_pk_bf16_f32 v146, v106, v107
	v_cvt_pk_bf16_f32 v147, v108, v109
	s_nop 1
	v_permlane16_swap_b32 v144, v146
	v_permlane16_swap_b32 v145, v147
	global_store_dwordx4 v137, v[144:147], s[94:95] sc1
	s_add_u32 s94, s94, 0x2000
	s_addc_u32 s95, s95, 0
	ds_read_b128 v[184:187], v136 offset:448
	ds_read_b128 v[188:191], v136 offset:4544
	s_waitcnt lgkmcnt(2)
	v_sub_f32_e32 v102, v102, v192
	v_mul_f32_e32 v102, v102, v193
	v_fma_f32 v102, v176, v102, v180
	v_sub_f32_e32 v103, v103, v192
	v_mul_f32_e32 v103, v103, v193
	v_fma_f32 v103, v177, v103, v181
	v_sub_f32_e32 v104, v104, v192
	v_mul_f32_e32 v104, v104, v193
	v_fma_f32 v104, v178, v104, v182
	v_sub_f32_e32 v105, v105, v192
	v_mul_f32_e32 v105, v105, v193
	v_fma_f32 v105, v179, v105, v183
	v_cvt_pk_bf16_f32 v152, v102, v103
	v_cvt_pk_bf16_f32 v153, v104, v105
	s_waitcnt lgkmcnt(0)
	v_sub_f32_e32 v66, v66, v192
	v_mul_f32_e32 v66, v66, v193
	v_fma_f32 v66, v184, v66, v188
	v_sub_f32_e32 v67, v67, v192
	v_mul_f32_e32 v67, v67, v193
	v_fma_f32 v67, v185, v67, v189
	v_sub_f32_e32 v68, v68, v192
	v_mul_f32_e32 v68, v68, v193
	v_fma_f32 v68, v186, v68, v190
	v_sub_f32_e32 v69, v69, v192
	v_mul_f32_e32 v69, v69, v193
	v_fma_f32 v69, v187, v69, v191
	v_cvt_pk_bf16_f32 v154, v66, v67
	v_cvt_pk_bf16_f32 v155, v68, v69
	s_nop 1
	v_permlane16_swap_b32 v152, v154
	v_permlane16_swap_b32 v153, v155
	global_store_dwordx4 v137, v[152:155], s[94:95] sc1
	s_waitcnt vmcnt(16) lgkmcnt(0)
	s_barrier
; DI void unit_O(const Params& p, char* lds, int l, int tile, int glu_tiles, int tile_b) {
;     ...
;         float s2[2], ss2[2];
; #pragma unroll
;         for (int mh = 0; mh < 2; ++mh) {
;             const int mt = half * 2 + mh, rl = mh * 16 + l15;
;             float s = 0.f, ss = 0.f;
; #pragma unroll
;             for (int nt = 0; nt < 8; ++nt) {
;                 f32x4 xr;
;                 if (l == 0) {
;                     const int chunk = wid * 32 + nt * 4 + quad;
;                     xr = *(const f32x4*)(XR + rl * 4096 + ((chunk ^ l15) << 4));
;                 } else {
;                     const u32x2 hb = *(const u32x2*)(XR + ((wid * 4 + (nt >> 1)) * 32 + rl) * 64 + (nt & 1) * 32 + quad * 8);
;                     xr = (f32x4){bf2f(hb[0] & 0xffffu), bf2f(hb[0] >> 16), bf2f(hb[1] & 0xffffu), bf2f(hb[1] >> 16)};
;                 }
; #pragma unroll
;                 for (int i = 0; i < 4; ++i) { const float v = acc[mt][nt][i] + DN_ALPHA * xr[i]; acc[mt][nt][i] = v; s += v; ss += v * v; }
;             }
;             s2[mh] = s; ss2[mh] = ss;
;         }
; #pragma unroll
;         for (int mh = 0; mh < 2; ++mh) { s2[mh] += __shfl_xor(s2[mh], 16); ss2[mh] += __shfl_xor(ss2[mh], 16); }
; #pragma unroll
;         for (int mh = 0; mh < 2; ++mh) { s2[mh] += __shfl_xor(s2[mh], 32); ss2[mh] += __shfl_xor(ss2[mh], 32); }
;         if (quad == 0) {
; #pragma unroll
;             for (int mh = 0; mh < 2; ++mh) *(f32x2*)&red[((mh * 16 + l15) * 8 + wid) * 2] = (f32x2){s2[mh], ss2[mh]};
;         }
;         __syncthreads();
;         if (half == 0) issue_x(1);
; #pragma unroll
;         for (int mh = 0; mh < 2; ++mh) {
;             const int mt = half * 2 + mh, rl = mh * 16 + l15, row = mt * 16 + l15;
;             float s = 0.f, ss = 0.f;
; #pragma unroll
;             for (int w = 0; w < 4; ++w) { const f32x4 v = *(const f32x4*)&red[rl * 16 + 4 * w]; s += v[0] + v[2]; ss += v[1] + v[3]; }
;             const float mu = s * (1.f / 1024.f);
;             const float var = ss * (1.f / 1024.f) - mu * mu;
;             const float rs = rsqrtf(var + LN_EPS);
;             float* orow = xo + (r0 + row) * 1024 + wid * 128 + quad * 4;
;             bf16_t* brow = xbo + xb_off((int)r0 + row, wid * 128) + quad * 4;
;             const float* gp = GB + wid * 128 + quad * 4;
; #pragma unroll
;             for (int nt = 0; nt < 8; ++nt) {
	ds_read_b128 v[144:147], v200
	ds_read_b128 v[148:151], v201
	ds_read_b128 v[152:155], v202
	ds_read_b128 v[156:159], v203
	ds_read_b128 v[160:163], v200 offset:256
	ds_read_b128 v[164:167], v201 offset:256
	ds_read_b128 v[168:171], v202 offset:256
	ds_read_b128 v[172:175], v203 offset:256
	s_waitcnt lgkmcnt(7)
	v_fmac_f32_e32 v34, s58, v144
	v_fmac_f32_e32 v35, s58, v145
	v_fmac_f32_e32 v36, s58, v146
	v_fmac_f32_e32 v37, s58, v147
	v_mov_b32_e32 v196, v34
	v_mul_f32_e32 v197, v34, v34
	v_mov_b32_e32 v130, v35
	v_mul_f32_e32 v142, v35, v35
	v_add_f32_e32 v196, v196, v36
	v_fmac_f32_e32 v197, v36, v36
	v_add_f32_e32 v130, v130, v37
	v_fmac_f32_e32 v142, v37, v37
	s_waitcnt lgkmcnt(6)
	v_fmac_f32_e32 v30, s58, v148
	v_fmac_f32_e32 v31, s58, v149
	v_fmac_f32_e32 v32, s58, v150
	v_fmac_f32_e32 v33, s58, v151
	v_add_f32_e32 v196, v196, v30
	v_fmac_f32_e32 v197, v30, v30
	v_add_f32_e32 v130, v130, v31
	v_fmac_f32_e32 v142, v31, v31
	v_add_f32_e32 v196, v196, v32
	v_fmac_f32_e32 v197, v32, v32
	v_add_f32_e32 v130, v130, v33
	v_fmac_f32_e32 v142, v33, v33
	s_waitcnt lgkmcnt(5)
	v_fmac_f32_e32 v26, s58, v152
	v_fmac_f32_e32 v27, s58, v153
	v_fmac_f32_e32 v28, s58, v154
	v_fmac_f32_e32 v29, s58, v155
	v_add_f32_e32 v196, v196, v26
	v_fmac_f32_e32 v197, v26, v26
	v_add_f32_e32 v130, v130, v27
	v_fmac_f32_e32 v142, v27, v27
	v_add_f32_e32 v196, v196, v28
	v_fmac_f32_e32 v197, v28, v28
	v_add_f32_e32 v130, v130, v29
	v_fmac_f32_e32 v142, v29, v29
	s_waitcnt lgkmcnt(4)
	v_fmac_f32_e32 v22, s58, v156
	v_fmac_f32_e32 v23, s58, v157
	v_fmac_f32_e32 v24, s58, v158
	v_fmac_f32_e32 v25, s58, v159
	v_add_f32_e32 v196, v196, v22
	v_fmac_f32_e32 v197, v22, v22
	v_add_f32_e32 v130, v130, v23
	v_fmac_f32_e32 v142, v23, v23
	v_add_f32_e32 v196, v196, v24
	v_fmac_f32_e32 v197, v24, v24
	v_add_f32_e32 v130, v130, v25
	v_fmac_f32_e32 v142, v25, v25
	s_waitcnt lgkmcnt(3)
	v_fmac_f32_e32 v18, s58, v160
	v_fmac_f32_e32 v19, s58, v161
	v_fmac_f32_e32 v20, s58, v162
	v_fmac_f32_e32 v21, s58, v163
	v_add_f32_e32 v196, v196, v18
	v_fmac_f32_e32 v197, v18, v18
	v_add_f32_e32 v130, v130, v19
	v_fmac_f32_e32 v142, v19, v19
	v_add_f32_e32 v196, v196, v20
	v_fmac_f32_e32 v197, v20, v20
	v_add_f32_e32 v130, v130, v21
	v_fmac_f32_e32 v142, v21, v21
	s_waitcnt lgkmcnt(2)
	v_fmac_f32_e32 v14, s58, v164
	v_fmac_f32_e32 v15, s58, v165
	v_fmac_f32_e32 v16, s58, v166
	v_fmac_f32_e32 v17, s58, v167
	v_add_f32_e32 v196, v196, v14
	v_fmac_f32_e32 v197, v14, v14
	v_add_f32_e32 v130, v130, v15
	v_fmac_f32_e32 v142, v15, v15
	v_add_f32_e32 v196, v196, v16
	v_fmac_f32_e32 v197, v16, v16
	v_add_f32_e32 v130, v130, v17
	v_fmac_f32_e32 v142, v17, v17
	s_waitcnt lgkmcnt(1)
	v_fmac_f32_e32 v10, s58, v168
	v_fmac_f32_e32 v11, s58, v169
	v_fmac_f32_e32 v12, s58, v170
	v_fmac_f32_e32 v13, s58, v171
	v_add_f32_e32 v196, v196, v10
	v_fmac_f32_e32 v197, v10, v10
	v_add_f32_e32 v130, v130, v11
	v_fmac_f32_e32 v142, v11, v11
	v_add_f32_e32 v196, v196, v12
	v_fmac_f32_e32 v197, v12, v12
	v_add_f32_e32 v130, v130, v13
	v_fmac_f32_e32 v142, v13, v13
	s_waitcnt lgkmcnt(0)
	v_fmac_f32_e32 v6, s58, v172
	v_fmac_f32_e32 v7, s58, v173
	v_fmac_f32_e32 v8, s58, v174
	v_fmac_f32_e32 v9, s58, v175
	v_add_f32_e32 v196, v196, v6
	v_fmac_f32_e32 v197, v6, v6
	v_add_f32_e32 v130, v130, v7
	v_fmac_f32_e32 v142, v7, v7
	v_add_f32_e32 v196, v196, v8
	v_fmac_f32_e32 v197, v8, v8
	v_add_f32_e32 v130, v130, v9
	v_fmac_f32_e32 v142, v9, v9
	v_add_f32_e32 v196, v196, v130
	v_add_f32_e32 v197, v197, v142
	v_mov_b32_e32 v198, v196
	v_mov_b32_e32 v199, v197
	s_nop 1
	v_permlane16_swap_b32 v198, v196
	v_permlane16_swap_b32 v199, v197
	v_add_f32_e32 v196, v196, v198
	v_add_f32_e32 v197, v197, v199
	v_mov_b32_e32 v198, v196
	v_mov_b32_e32 v199, v197
	s_nop 1
	v_permlane32_swap_b32 v198, v196
	v_permlane32_swap_b32 v199, v197
	v_add_f32_e32 v196, v196, v198
	v_add_f32_e32 v197, v197, v199
	s_mov_b64 exec, 0xffff
	ds_write_b64 v134, v[196:197]
	s_mov_b64 exec, -1
	s_waitcnt lgkmcnt(0)
	s_barrier
	ds_read_b128 v[160:163], v135 offset:0
	ds_read_b128 v[164:167], v135 offset:16
	ds_read_b128 v[168:171], v135 offset:32
	ds_read_b128 v[172:175], v135 offset:48
	s_waitcnt lgkmcnt(0)
	v_add_f32_e32 v160, v160, v162
	v_add_f32_e32 v161, v161, v163
	v_add_f32_e32 v164, v164, v166
	v_add_f32_e32 v165, v165, v167
	v_add_f32_e32 v168, v168, v170
	v_add_f32_e32 v169, v169, v171
	v_add_f32_e32 v172, v172, v174
	v_add_f32_e32 v173, v173, v175
	v_add_f32_e32 v160, v160, v164
	v_add_f32_e32 v161, v161, v165
	v_add_f32_e32 v168, v168, v172
	v_add_f32_e32 v169, v169, v173
	v_add_f32_e32 v160, v160, v168
	v_add_f32_e32 v161, v161, v169
	v_mul_f32_e32 v192, 0x3a800000, v160
	v_mul_f32_e32 v193, 0x3a800000, v161
	v_fma_f32 v193, -v192, v192, v193
	v_add_f32_e32 v193, 0x3727c5ac, v193
	v_rsq_f32_e32 v193, v193
	s_nop 0
	s_add_u32 s94, s78, 0x800
	s_addc_u32 s95, s79, 0
	ds_read_b128 v[176:179], v136
	ds_read_b128 v[180:183], v136 offset:4096
	ds_read_b128 v[184:187], v136 offset:64
	ds_read_b128 v[188:191], v136 offset:4160
	s_waitcnt lgkmcnt(2)
	v_sub_f32_e32 v34, v34, v192
	v_mul_f32_e32 v34, v34, v193
	v_fma_f32 v34, v176, v34, v180
	v_sub_f32_e32 v35, v35, v192
	v_mul_f32_e32 v35, v35, v193
	v_fma_f32 v35, v177, v35, v181
	v_sub_f32_e32 v36, v36, v192
	v_mul_f32_e32 v36, v36, v193
	v_fma_f32 v36, v178, v36, v182
	v_sub_f32_e32 v37, v37, v192
	v_mul_f32_e32 v37, v37, v193
	v_fma_f32 v37, v179, v37, v183
	v_cvt_pk_bf16_f32 v144, v34, v35
	v_cvt_pk_bf16_f32 v145, v36, v37
	ds_read_b128 v[176:179], v136 offset:128
	ds_read_b128 v[180:183], v136 offset:4224
	s_waitcnt lgkmcnt(2)
; DI unsigned pk2(float lo, float hi) { const f32x2 v = {lo, hi}; const bf16x2_t b = __builtin_convertvector(v, bf16x2_t); return __builtin_bit_cast(unsigned, b); }
; DI size_t xb_off(int tok, int col) { return ((size_t)(((tok >> 7) * 32 + (col >> 5)) * 128 + (tok & 127))) * 32 + (col & 31); }
; DI void unit_O(const Params& p, char* lds, int l, int tile, int glu_tiles, int tile_b) {
;     ...
;             float* orow = xo + (r0 + row) * 1024 + wid * 128 + quad * 4;
;             bf16_t* brow = xbo + xb_off((int)r0 + row, wid * 128) + quad * 4;
;             const float* gp = GB + wid * 128 + quad * 4;
; #pragma unroll
;             for (int nt = 0; nt < 8; ++nt) {
;                 const f32x4 g = *(const f32x4*)(gp + nt * 16), bb = *(const f32x4*)(gp + 1024 + nt * 16);
;                 f32x4 o;
; #pragma unroll
;                 for (int i = 0; i < 4; ++i) o[i] = (acc[mt][nt][i] - mu) * rs * g[i] + bb[i];
;                 if (l == 0) *(u32x2*)(brow + (nt >> 1) * 4096 + (nt & 1) * 16) = (u32x2){pk2(o[0], o[1]), pk2(o[2], o[3])};
;                 else *(f32x4*)(orow + nt * 16) = o;
;             }
;         }
	v_sub_f32_e32 v30, v30, v192
	v_mul_f32_e32 v30, v30, v193
	v_fma_f32 v30, v184, v30, v188
	v_sub_f32_e32 v31, v31, v192
	v_mul_f32_e32 v31, v31, v193
	v_fma_f32 v31, v185, v31, v189
	v_sub_f32_e32 v32, v32, v192
	v_mul_f32_e32 v32, v32, v193
	v_fma_f32 v32, v186, v32, v190
	v_sub_f32_e32 v33, v33, v192
	v_mul_f32_e32 v33, v33, v193
	v_fma_f32 v33, v187, v33, v191
	v_cvt_pk_bf16_f32 v146, v30, v31
	v_cvt_pk_bf16_f32 v147, v32, v33
	s_nop 1
	v_permlane16_swap_b32 v144, v146
	v_permlane16_swap_b32 v145, v147
	global_store_dwordx4 v137, v[144:147], s[94:95] sc1
	s_add_u32 s94, s94, 0x2000
	s_addc_u32 s95, s95, 0
	ds_read_b128 v[184:187], v136 offset:192
	ds_read_b128 v[188:191], v136 offset:4288
	s_waitcnt lgkmcnt(2)
	v_sub_f32_e32 v26, v26, v192
	v_mul_f32_e32 v26, v26, v193
	v_fma_f32 v26, v176, v26, v180
	v_sub_f32_e32 v27, v27, v192
	v_mul_f32_e32 v27, v27, v193
	v_fma_f32 v27, v177, v27, v181
	v_sub_f32_e32 v28, v28, v192
	v_mul_f32_e32 v28, v28, v193
	v_fma_f32 v28, v178, v28, v182
	v_sub_f32_e32 v29, v29, v192
	v_mul_f32_e32 v29, v29, v193
	v_fma_f32 v29, v179, v29, v183
	v_cvt_pk_bf16_f32 v152, v26, v27
	v_cvt_pk_bf16_f32 v153, v28, v29
	ds_read_b128 v[176:179], v136 offset:256
	ds_read_b128 v[180:183], v136 offset:4352
	s_waitcnt lgkmcnt(2)
	v_sub_f32_e32 v22, v22, v192
	v_mul_f32_e32 v22, v22, v193
	v_fma_f32 v22, v184, v22, v188
	v_sub_f32_e32 v23, v23, v192
	v_mul_f32_e32 v23, v23, v193
	v_fma_f32 v23, v185, v23, v189
	v_sub_f32_e32 v24, v24, v192
	v_mul_f32_e32 v24, v24, v193
	v_fma_f32 v24, v186, v24, v190
	v_sub_f32_e32 v25, v25, v192
	v_mul_f32_e32 v25, v25, v193
	v_fma_f32 v25, v187, v25, v191
	v_cvt_pk_bf16_f32 v154, v22, v23
	v_cvt_pk_bf16_f32 v155, v24, v25
	s_nop 1
	v_permlane16_swap_b32 v152, v154
	v_permlane16_swap_b32 v153, v155
	global_store_dwordx4 v137, v[152:155], s[94:95] sc1
	s_add_u32 s94, s94, 0x2000
	s_addc_u32 s95, s95, 0
	ds_read_b128 v[184:187], v136 offset:320
	ds_read_b128 v[188:191], v136 offset:4416
	s_waitcnt lgkmcnt(2)
	v_sub_f32_e32 v18, v18, v192
	v_mul_f32_e32 v18, v18, v193
	v_fma_f32 v18, v176, v18, v180
	v_sub_f32_e32 v19, v19, v192
	v_mul_f32_e32 v19, v19, v193
	v_fma_f32 v19, v177, v19, v181
	v_sub_f32_e32 v20, v20, v192
	v_mul_f32_e32 v20, v20, v193
	v_fma_f32 v20, v178, v20, v182
	v_sub_f32_e32 v21, v21, v192
	v_mul_f32_e32 v21, v21, v193
	v_fma_f32 v21, v179, v21, v183
	v_cvt_pk_bf16_f32 v144, v18, v19
	v_cvt_pk_bf16_f32 v145, v20, v21
	ds_read_b128 v[176:179], v136 offset:384
	ds_read_b128 v[180:183], v136 offset:4480
	s_waitcnt lgkmcnt(2)
	v_sub_f32_e32 v14, v14, v192
	v_mul_f32_e32 v14, v14, v193
	v_fma_f32 v14, v184, v14, v188
	v_sub_f32_e32 v15, v15, v192
	v_mul_f32_e32 v15, v15, v193
	v_fma_f32 v15, v185, v15, v189
	v_sub_f32_e32 v16, v16, v192
	v_mul_f32_e32 v16, v16, v193
	v_fma_f32 v16, v186, v16, v190
	v_sub_f32_e32 v17, v17, v192
	v_mul_f32_e32 v17, v17, v193
	v_fma_f32 v17, v187, v17, v191
	v_cvt_pk_bf16_f32 v146, v14, v15
	v_cvt_pk_bf16_f32 v147, v16, v17
	s_nop 1
	v_permlane16_swap_b32 v144, v146
	v_permlane16_swap_b32 v145, v147
	global_store_dwordx4 v137, v[144:147], s[94:95] sc1
	s_add_u32 s94, s94, 0x2000
	s_addc_u32 s95, s95, 0
	ds_read_b128 v[184:187], v136 offset:448
	ds_read_b128 v[188:191], v136 offset:4544
	s_waitcnt lgkmcnt(2)
	v_sub_f32_e32 v10, v10, v192
	v_mul_f32_e32 v10, v10, v193
	v_fma_f32 v10, v176, v10, v180
	v_sub_f32_e32 v11, v11, v192
	v_mul_f32_e32 v11, v11, v193
	v_fma_f32 v11, v177, v11, v181
	v_sub_f32_e32 v12, v12, v192
	v_mul_f32_e32 v12, v12, v193
	v_fma_f32 v12, v178, v12, v182
	v_sub_f32_e32 v13, v13, v192
	v_mul_f32_e32 v13, v13, v193
	v_fma_f32 v13, v179, v13, v183
	v_cvt_pk_bf16_f32 v152, v10, v11
	v_cvt_pk_bf16_f32 v153, v12, v13
	s_waitcnt lgkmcnt(0)
	v_sub_f32_e32 v6, v6, v192
	v_mul_f32_e32 v6, v6, v193
	v_fma_f32 v6, v184, v6, v188
	v_sub_f32_e32 v7, v7, v192
	v_mul_f32_e32 v7, v7, v193
	v_fma_f32 v7, v185, v7, v189
	v_sub_f32_e32 v8, v8, v192
	v_mul_f32_e32 v8, v8, v193
	v_fma_f32 v8, v186, v8, v190
	v_sub_f32_e32 v9, v9, v192
	v_mul_f32_e32 v9, v9, v193
	v_fma_f32 v9, v187, v9, v191
	v_cvt_pk_bf16_f32 v154, v6, v7
	v_cvt_pk_bf16_f32 v155, v8, v9
	s_nop 1
	v_permlane16_swap_b32 v152, v154
	v_permlane16_swap_b32 v153, v155
	global_store_dwordx4 v137, v[152:155], s[94:95] sc1
	s_waitcnt vmcnt(8) lgkmcnt(0)
	s_barrier
; DI float bf2f(unsigned b) { return __uint_as_float(b << 16); }
; DI void unit_O(const Params& p, char* lds, int l, int tile, int glu_tiles, int tile_b) {
;     ...
;         float s2[2], ss2[2];
; #pragma unroll
;         for (int mh = 0; mh < 2; ++mh) {
;             const int mt = half * 2 + mh, rl = mh * 16 + l15;
;             float s = 0.f, ss = 0.f;
; #pragma unroll
;             for (int nt = 0; nt < 8; ++nt) {
;                 f32x4 xr;
;                 if (l == 0) {
;                     const int chunk = wid * 32 + nt * 4 + quad;
;                     xr = *(const f32x4*)(XR + rl * 4096 + ((chunk ^ l15) << 4));
;                 } else {
;                     const u32x2 hb = *(const u32x2*)(XR + ((wid * 4 + (nt >> 1)) * 32 + rl) * 64 + (nt & 1) * 32 + quad * 8);
;                     xr = (f32x4){bf2f(hb[0] & 0xffffu), bf2f(hb[0] >> 16), bf2f(hb[1] & 0xffffu), bf2f(hb[1] >> 16)};
;                 }
; #pragma unroll
;                 for (int i = 0; i < 4; ++i) { const float v = acc[mt][nt][i] + DN_ALPHA * xr[i]; acc[mt][nt][i] = v; s += v; ss += v * v; }
;             }
;             s2[mh] = s; ss2[mh] = ss;
;         }
; #pragma unroll
;         for (int mh = 0; mh < 2; ++mh) { s2[mh] += __shfl_xor(s2[mh], 16); ss2[mh] += __shfl_xor(ss2[mh], 16); }
; #pragma unroll
;         for (int mh = 0; mh < 2; ++mh) { s2[mh] += __shfl_xor(s2[mh], 32); ss2[mh] += __shfl_xor(ss2[mh], 32); }
;         if (quad == 0) {
; #pragma unroll
;             for (int mh = 0; mh < 2; ++mh) *(f32x2*)&red[((mh * 16 + l15) * 8 + wid) * 2] = (f32x2){s2[mh], ss2[mh]};
;         }
;         __syncthreads();
	ds_read_b128 v[144:147], v204
	ds_read_b128 v[148:151], v205
	ds_read_b128 v[152:155], v206
	ds_read_b128 v[156:159], v207
	ds_read_b128 v[160:163], v204 offset:256
	ds_read_b128 v[164:167], v205 offset:256
	ds_read_b128 v[168:171], v206 offset:256
	ds_read_b128 v[172:175], v207 offset:256
	s_waitcnt lgkmcnt(7)
	v_fmac_f32_e32 v62, s58, v144
	v_fmac_f32_e32 v63, s58, v145
	v_fmac_f32_e32 v64, s58, v146
	v_fmac_f32_e32 v65, s58, v147
	v_mov_b32_e32 v196, v62
	v_mul_f32_e32 v197, v62, v62
	v_mov_b32_e32 v130, v63
	v_mul_f32_e32 v142, v63, v63
	v_add_f32_e32 v196, v196, v64
	v_fmac_f32_e32 v197, v64, v64
	v_add_f32_e32 v130, v130, v65
	v_fmac_f32_e32 v142, v65, v65
	s_waitcnt lgkmcnt(6)
	v_fmac_f32_e32 v58, s58, v148
	v_fmac_f32_e32 v59, s58, v149
	v_fmac_f32_e32 v60, s58, v150
	v_fmac_f32_e32 v61, s58, v151
	v_add_f32_e32 v196, v196, v58
	v_fmac_f32_e32 v197, v58, v58
	v_add_f32_e32 v130, v130, v59
	v_fmac_f32_e32 v142, v59, v59
	v_add_f32_e32 v196, v196, v60
	v_fmac_f32_e32 v197, v60, v60
	v_add_f32_e32 v130, v130, v61
	v_fmac_f32_e32 v142, v61, v61
	s_waitcnt lgkmcnt(5)
	v_fmac_f32_e32 v54, s58, v152
	v_fmac_f32_e32 v55, s58, v153
	v_fmac_f32_e32 v56, s58, v154
	v_fmac_f32_e32 v57, s58, v155
	v_add_f32_e32 v196, v196, v54
	v_fmac_f32_e32 v197, v54, v54
	v_add_f32_e32 v130, v130, v55
	v_fmac_f32_e32 v142, v55, v55
	v_add_f32_e32 v196, v196, v56
	v_fmac_f32_e32 v197, v56, v56
	v_add_f32_e32 v130, v130, v57
	v_fmac_f32_e32 v142, v57, v57
	s_waitcnt lgkmcnt(4)
	v_fmac_f32_e32 v50, s58, v156
	v_fmac_f32_e32 v51, s58, v157
	v_fmac_f32_e32 v52, s58, v158
	v_fmac_f32_e32 v53, s58, v159
	v_add_f32_e32 v196, v196, v50
	v_fmac_f32_e32 v197, v50, v50
	v_add_f32_e32 v130, v130, v51
	v_fmac_f32_e32 v142, v51, v51
	v_add_f32_e32 v196, v196, v52
	v_fmac_f32_e32 v197, v52, v52
	v_add_f32_e32 v130, v130, v53
	v_fmac_f32_e32 v142, v53, v53
	s_waitcnt lgkmcnt(3)
	v_fmac_f32_e32 v46, s58, v160
	v_fmac_f32_e32 v47, s58, v161
	v_fmac_f32_e32 v48, s58, v162
	v_fmac_f32_e32 v49, s58, v163
	v_add_f32_e32 v196, v196, v46
	v_fmac_f32_e32 v197, v46, v46
	v_add_f32_e32 v130, v130, v47
	v_fmac_f32_e32 v142, v47, v47
	v_add_f32_e32 v196, v196, v48
	v_fmac_f32_e32 v197, v48, v48
	v_add_f32_e32 v130, v130, v49
	v_fmac_f32_e32 v142, v49, v49
	s_waitcnt lgkmcnt(2)
	v_fmac_f32_e32 v42, s58, v164
	v_fmac_f32_e32 v43, s58, v165
	v_fmac_f32_e32 v44, s58, v166
	v_fmac_f32_e32 v45, s58, v167
	v_add_f32_e32 v196, v196, v42
	v_fmac_f32_e32 v197, v42, v42
	v_add_f32_e32 v130, v130, v43
	v_fmac_f32_e32 v142, v43, v43
	v_add_f32_e32 v196, v196, v44
	v_fmac_f32_e32 v197, v44, v44
	v_add_f32_e32 v130, v130, v45
	v_fmac_f32_e32 v142, v45, v45
	s_waitcnt lgkmcnt(1)
	v_fmac_f32_e32 v38, s58, v168
	v_fmac_f32_e32 v39, s58, v169
	v_fmac_f32_e32 v40, s58, v170
	v_fmac_f32_e32 v41, s58, v171
	v_add_f32_e32 v196, v196, v38
	v_fmac_f32_e32 v197, v38, v38
	v_add_f32_e32 v130, v130, v39
	v_fmac_f32_e32 v142, v39, v39
	v_add_f32_e32 v196, v196, v40
	v_fmac_f32_e32 v197, v40, v40
	v_add_f32_e32 v130, v130, v41
	v_fmac_f32_e32 v142, v41, v41
	s_waitcnt lgkmcnt(0)
	v_fmac_f32_e32 v2, s58, v172
	v_fmac_f32_e32 v3, s58, v173
	v_fmac_f32_e32 v4, s58, v174
	v_fmac_f32_e32 v5, s58, v175
	v_add_f32_e32 v196, v196, v2
	v_fmac_f32_e32 v197, v2, v2
	v_add_f32_e32 v130, v130, v3
	v_fmac_f32_e32 v142, v3, v3
	v_add_f32_e32 v196, v196, v4
	v_fmac_f32_e32 v197, v4, v4
	v_add_f32_e32 v130, v130, v5
	v_fmac_f32_e32 v142, v5, v5
	v_add_f32_e32 v196, v196, v130
	v_add_f32_e32 v197, v197, v142
	v_mov_b32_e32 v198, v196
	v_mov_b32_e32 v199, v197
	s_nop 1
	v_permlane16_swap_b32 v198, v196
	v_permlane16_swap_b32 v199, v197
	v_add_f32_e32 v196, v196, v198
	v_add_f32_e32 v197, v197, v199
	v_mov_b32_e32 v198, v196
	v_mov_b32_e32 v199, v197
	s_nop 1
	v_permlane32_swap_b32 v198, v196
	v_permlane32_swap_b32 v199, v197
	v_add_f32_e32 v196, v196, v198
	v_add_f32_e32 v197, v197, v199
	s_mov_b64 exec, 0xffff
	ds_write_b64 v134, v[196:197]
	s_mov_b64 exec, -1
	s_waitcnt lgkmcnt(0)
	s_barrier
; DI unsigned pk2(float lo, float hi) { const f32x2 v = {lo, hi}; const bf16x2_t b = __builtin_convertvector(v, bf16x2_t); return __builtin_bit_cast(unsigned, b); }
; DI size_t xb_off(int tok, int col) { return ((size_t)(((tok >> 7) * 32 + (col >> 5)) * 128 + (tok & 127))) * 32 + (col & 31); }
; DI void unit_O(const Params& p, char* lds, int l, int tile, int glu_tiles, int tile_b) {
;     ...
; #pragma unroll
;         for (int mh = 0; mh < 2; ++mh) {
;             const int mt = half * 2 + mh, rl = mh * 16 + l15, row = mt * 16 + l15;
;             float s = 0.f, ss = 0.f;
; #pragma unroll
;             for (int w = 0; w < 4; ++w) { const f32x4 v = *(const f32x4*)&red[rl * 16 + 4 * w]; s += v[0] + v[2]; ss += v[1] + v[3]; }
;             const float mu = s * (1.f / 1024.f);
;             const float var = ss * (1.f / 1024.f) - mu * mu;
;             const float rs = rsqrtf(var + LN_EPS);
;             float* orow = xo + (r0 + row) * 1024 + wid * 128 + quad * 4;
;             bf16_t* brow = xbo + xb_off((int)r0 + row, wid * 128) + quad * 4;
;             const float* gp = GB + wid * 128 + quad * 4;
; #pragma unroll
;             for (int nt = 0; nt < 8; ++nt) {
;                 const f32x4 g = *(const f32x4*)(gp + nt * 16), bb = *(const f32x4*)(gp + 1024 + nt * 16);
;                 f32x4 o;
; #pragma unroll
;                 for (int i = 0; i < 4; ++i) o[i] = (acc[mt][nt][i] - mu) * rs * g[i] + bb[i];
;                 if (l == 0) *(u32x2*)(brow + (nt >> 1) * 4096 + (nt & 1) * 16) = (u32x2){pk2(o[0], o[1]), pk2(o[2], o[3])};
;                 else *(f32x4*)(orow + nt * 16) = o;
;             }
;         }
	ds_read_b128 v[160:163], v135 offset:0
	ds_read_b128 v[164:167], v135 offset:16
	ds_read_b128 v[168:171], v135 offset:32
	ds_read_b128 v[172:175], v135 offset:48
	s_waitcnt lgkmcnt(0)
	v_add_f32_e32 v160, v160, v162
	v_add_f32_e32 v161, v161, v163
	v_add_f32_e32 v164, v164, v166
	v_add_f32_e32 v165, v165, v167
	v_add_f32_e32 v168, v168, v170
	v_add_f32_e32 v169, v169, v171
	v_add_f32_e32 v172, v172, v174
	v_add_f32_e32 v173, v173, v175
	v_add_f32_e32 v160, v160, v164
	v_add_f32_e32 v161, v161, v165
	v_add_f32_e32 v168, v168, v172
	v_add_f32_e32 v169, v169, v173
	v_add_f32_e32 v160, v160, v168
	v_add_f32_e32 v161, v161, v169
	v_mul_f32_e32 v192, 0x3a800000, v160
	v_mul_f32_e32 v193, 0x3a800000, v161
	v_fma_f32 v193, -v192, v192, v193
	v_add_f32_e32 v193, 0x3727c5ac, v193
	v_rsq_f32_e32 v193, v193
	s_nop 0
	s_add_u32 s94, s78, 0xc00
	s_addc_u32 s95, s79, 0
	ds_read_b128 v[176:179], v136
	ds_read_b128 v[180:183], v136 offset:4096
	ds_read_b128 v[184:187], v136 offset:64
	ds_read_b128 v[188:191], v136 offset:4160
	s_waitcnt lgkmcnt(2)
	v_sub_f32_e32 v62, v62, v192
	v_mul_f32_e32 v62, v62, v193
	v_fma_f32 v62, v176, v62, v180
	v_sub_f32_e32 v63, v63, v192
	v_mul_f32_e32 v63, v63, v193
	v_fma_f32 v63, v177, v63, v181
	v_sub_f32_e32 v64, v64, v192
	v_mul_f32_e32 v64, v64, v193
	v_fma_f32 v64, v178, v64, v182
	v_sub_f32_e32 v65, v65, v192
	v_mul_f32_e32 v65, v65, v193
	v_fma_f32 v65, v179, v65, v183
	v_cvt_pk_bf16_f32 v144, v62, v63
	v_cvt_pk_bf16_f32 v145, v64, v65
	ds_read_b128 v[176:179], v136 offset:128
	ds_read_b128 v[180:183], v136 offset:4224
	s_waitcnt lgkmcnt(2)
	v_sub_f32_e32 v58, v58, v192
	v_mul_f32_e32 v58, v58, v193
	v_fma_f32 v58, v184, v58, v188
	v_sub_f32_e32 v59, v59, v192
	v_mul_f32_e32 v59, v59, v193
	v_fma_f32 v59, v185, v59, v189
	v_sub_f32_e32 v60, v60, v192
	v_mul_f32_e32 v60, v60, v193
	v_fma_f32 v60, v186, v60, v190
	v_sub_f32_e32 v61, v61, v192
	v_mul_f32_e32 v61, v61, v193
	v_fma_f32 v61, v187, v61, v191
	v_cvt_pk_bf16_f32 v146, v58, v59
	v_cvt_pk_bf16_f32 v147, v60, v61
	s_nop 1
	v_permlane16_swap_b32 v144, v146
	v_permlane16_swap_b32 v145, v147
	global_store_dwordx4 v137, v[144:147], s[94:95]
	s_add_u32 s94, s94, 0x2000
	s_addc_u32 s95, s95, 0
	ds_read_b128 v[184:187], v136 offset:192
	ds_read_b128 v[188:191], v136 offset:4288
	s_waitcnt lgkmcnt(2)
	v_sub_f32_e32 v54, v54, v192
	v_mul_f32_e32 v54, v54, v193
	v_fma_f32 v54, v176, v54, v180
	v_sub_f32_e32 v55, v55, v192
	v_mul_f32_e32 v55, v55, v193
	v_fma_f32 v55, v177, v55, v181
	v_sub_f32_e32 v56, v56, v192
	v_mul_f32_e32 v56, v56, v193
	v_fma_f32 v56, v178, v56, v182
	v_sub_f32_e32 v57, v57, v192
	v_mul_f32_e32 v57, v57, v193
	v_fma_f32 v57, v179, v57, v183
	v_cvt_pk_bf16_f32 v152, v54, v55
	v_cvt_pk_bf16_f32 v153, v56, v57
	ds_read_b128 v[176:179], v136 offset:256
	ds_read_b128 v[180:183], v136 offset:4352
	s_waitcnt lgkmcnt(2)
	v_sub_f32_e32 v50, v50, v192
	v_mul_f32_e32 v50, v50, v193
	v_fma_f32 v50, v184, v50, v188
	v_sub_f32_e32 v51, v51, v192
	v_mul_f32_e32 v51, v51, v193
	v_fma_f32 v51, v185, v51, v189
	v_sub_f32_e32 v52, v52, v192
	v_mul_f32_e32 v52, v52, v193
	v_fma_f32 v52, v186, v52, v190
	v_sub_f32_e32 v53, v53, v192
	v_mul_f32_e32 v53, v53, v193
	v_fma_f32 v53, v187, v53, v191
	v_cvt_pk_bf16_f32 v154, v50, v51
	v_cvt_pk_bf16_f32 v155, v52, v53
	s_nop 1
	v_permlane16_swap_b32 v152, v154
	v_permlane16_swap_b32 v153, v155
	global_store_dwordx4 v137, v[152:155], s[94:95]
	s_add_u32 s94, s94, 0x2000
	s_addc_u32 s95, s95, 0
	ds_read_b128 v[184:187], v136 offset:320
	ds_read_b128 v[188:191], v136 offset:4416
	s_waitcnt lgkmcnt(2)
	v_sub_f32_e32 v46, v46, v192
	v_mul_f32_e32 v46, v46, v193
	v_fma_f32 v46, v176, v46, v180
	v_sub_f32_e32 v47, v47, v192
	v_mul_f32_e32 v47, v47, v193
	v_fma_f32 v47, v177, v47, v181
	v_sub_f32_e32 v48, v48, v192
	v_mul_f32_e32 v48, v48, v193
	v_fma_f32 v48, v178, v48, v182
	v_sub_f32_e32 v49, v49, v192
	v_mul_f32_e32 v49, v49, v193
	v_fma_f32 v49, v179, v49, v183
	v_cvt_pk_bf16_f32 v144, v46, v47
	v_cvt_pk_bf16_f32 v145, v48, v49
	ds_read_b128 v[176:179], v136 offset:384
	ds_read_b128 v[180:183], v136 offset:4480
	s_waitcnt lgkmcnt(2)
	v_sub_f32_e32 v42, v42, v192
	v_mul_f32_e32 v42, v42, v193
	v_fma_f32 v42, v184, v42, v188
	v_sub_f32_e32 v43, v43, v192
	v_mul_f32_e32 v43, v43, v193
	v_fma_f32 v43, v185, v43, v189
	v_sub_f32_e32 v44, v44, v192
	v_mul_f32_e32 v44, v44, v193
	v_fma_f32 v44, v186, v44, v190
	v_sub_f32_e32 v45, v45, v192
	v_mul_f32_e32 v45, v45, v193
	v_fma_f32 v45, v187, v45, v191
	v_cvt_pk_bf16_f32 v146, v42, v43
	v_cvt_pk_bf16_f32 v147, v44, v45
	s_nop 1
	v_permlane16_swap_b32 v144, v146
	v_permlane16_swap_b32 v145, v147
	global_store_dwordx4 v137, v[144:147], s[94:95]
	s_add_u32 s94, s94, 0x2000
	s_addc_u32 s95, s95, 0
	ds_read_b128 v[184:187], v136 offset:448
	ds_read_b128 v[188:191], v136 offset:4544
	s_waitcnt lgkmcnt(2)
	v_sub_f32_e32 v38, v38, v192
	v_mul_f32_e32 v38, v38, v193
	v_fma_f32 v38, v176, v38, v180
	v_sub_f32_e32 v39, v39, v192
	v_mul_f32_e32 v39, v39, v193
	v_fma_f32 v39, v177, v39, v181
	v_sub_f32_e32 v40, v40, v192
	v_mul_f32_e32 v40, v40, v193
	v_fma_f32 v40, v178, v40, v182
	v_sub_f32_e32 v41, v41, v192
	v_mul_f32_e32 v41, v41, v193
	v_fma_f32 v41, v179, v41, v183
	v_cvt_pk_bf16_f32 v152, v38, v39
	v_cvt_pk_bf16_f32 v153, v40, v41
	s_waitcnt lgkmcnt(0)
	v_sub_f32_e32 v2, v2, v192
	v_mul_f32_e32 v2, v2, v193
	v_fma_f32 v2, v184, v2, v188
	v_sub_f32_e32 v3, v3, v192
	v_mul_f32_e32 v3, v3, v193
	v_fma_f32 v3, v185, v3, v189
	v_sub_f32_e32 v4, v4, v192
	v_mul_f32_e32 v4, v4, v193
	v_fma_f32 v4, v186, v4, v190
	v_sub_f32_e32 v5, v5, v192
	v_mul_f32_e32 v5, v5, v193
	v_fma_f32 v5, v187, v5, v191
	v_cvt_pk_bf16_f32 v154, v2, v3
	v_cvt_pk_bf16_f32 v155, v4, v5
	s_nop 1
	v_permlane16_swap_b32 v152, v154
	v_permlane16_swap_b32 v153, v155
	global_store_dwordx4 v137, v[152:155], s[94:95]
	s_branch .Le2_done
